# w_out epilogue: f32 residual loads (16 B per lane at 32-byte lane stride) replaced by full-sector loads + v_permlane32_swap/v_permlane16_swap redistribution
# baseline (speedup 1.0000x reference)
; template <class T> DI T gld_nt(const void* base, unsigned off) { return __builtin_nontemporal_load((const T*)((const char*)base + off)); }
; DI u32x4 pk8(const f32x4& a, const f32x4& b) { u32x4 w; w.x = pk2(a[0], a[1]); w.y = pk2(a[2], a[3]); w.z = pk2(b[0], b[1]); w.w = pk2(b[2], b[3]); return w; }
; DI void unpk8(const u32x4& w, f32x4& a, f32x4& b) { a[0] = bf_lo(w.x); a[1] = bf_hi(w.x); a[2] = bf_lo(w.y); a[3] = bf_hi(w.y); b[0] = bf_lo(w.z); b[1] = bf_hi(w.z); b[2] = bf_lo(w.w); b[3] = bf_hi(w.w); }
;   DI void operator()(g8::Acc& acc, int pm, int pn, int wr, int wc, int fr, int fq) const {
;     ...
;     for (int ai = 0; ai < 2; ++ai)
; #pragma unroll
;       for (int m = 0; m < 4; ++m) {
;         const int row = pm * BM + ai * HALF + wr * 64 + m * 16 + fr; float s = 0.f; u32x4 wv[2];
; #pragma unroll
;         for (int bj = 0; bj < 2; ++bj) {
;           const int col8 = pn * BM + wc * 64 + bj * 32 + fq * 8; const unsigned eo = (unsigned)row * DM + (unsigned)col8;
;           f32x4 r0, r1;
;           if (resf) { r0 = gld_nt<f32x4>(resf, eo * 4u); r1 = gld_nt<f32x4>(resf, eo * 4u + 16u); }
;           else unpk8(gld_nt<u32x4>(resb, eo * 2u), r0, r1);
;           const f32x4 o0 = r0 + acc[ai][bj][m][0], o1 = r1 + acc[ai][bj][m][1];
;           if (outf) { gst<f32x4>(outf, eo * 4u, o0); gst<f32x4>(outf, eo * 4u + 16u, o1); }
;           wv[bj] = pk8(o0, o1);
;           s += o0[0] * o0[0] + o0[1] * o0[1] + o0[2] * o0[2] + o0[3] * o0[3] + o1[0] * o1[0] + o1[1] * o1[1] + o1[2] * o1[2] + o1[3] * o1[3];
;         }
;         if (outb) st_rows16(outb, DM * 2u, (unsigned)(row - fr), (unsigned)(pn * BM + wc * 64), fr, fq, wv[0], wv[1]);
;         s += __shfl_xor(s, 16); s += __shfl_xor(s, 32);
;         if (fq == 0) atomicAdd(ssq + row, s);
.LBB0_554:
	s_lshl_b32 s21, s58, 8
	s_add_i32 s21, s21, s11
	v_lshl_or_b32 v141, s54, 8, v144
	v_or_b32_e32 v140, s21, v142
	v_lshlrev_b32_e32 v154, 2, v141
	v_lshl_add_u32 v248, v140, 12, v154
	v_mbcnt_lo_u32_b32 v250, -1, 0
	v_mbcnt_hi_u32_b32 v250, -1, v250
	v_and_b32_e32 v250, 48, v250
	v_sub_u32_e32 v248, v248, v250
	global_load_dwordx4 v[176:179], v248, s[16:17] nt
	global_load_dwordx4 v[180:183], v248, s[16:17] offset:64 nt
	global_load_dwordx4 v[184:187], v248, s[16:17] offset:128 nt
	global_load_dwordx4 v[188:191], v248, s[16:17] offset:192 nt
	v_add_u32_e32 v249, 0x10000, v248
	global_load_dwordx4 v[192:195], v249, s[16:17] nt
	global_load_dwordx4 v[196:199], v249, s[16:17] offset:64 nt
	global_load_dwordx4 v[200:203], v249, s[16:17] offset:128 nt
	global_load_dwordx4 v[204:207], v249, s[16:17] offset:192 nt
	v_add_u32_e32 v249, 0x20000, v248
	global_load_dwordx4 v[216:219], v249, s[16:17] nt
	global_load_dwordx4 v[220:223], v249, s[16:17] offset:64 nt
	global_load_dwordx4 v[224:227], v249, s[16:17] offset:128 nt
	global_load_dwordx4 v[228:231], v249, s[16:17] offset:192 nt
	v_add_u32_e32 v249, 0x30000, v248
	global_load_dwordx4 v[232:235], v249, s[16:17] nt
	global_load_dwordx4 v[236:239], v249, s[16:17] offset:64 nt
	global_load_dwordx4 v[240:243], v249, s[16:17] offset:128 nt
	global_load_dwordx4 v[244:247], v249, s[16:17] offset:192 nt
	v_or_b32_e32 v152, v141, v146
	v_or_b32_e32 v141, v141, v147
	v_lshlrev_b32_e32 v153, 1, v152
	v_lshl_add_u32 v152, v141, 1, v151
	v_mov_b32_e32 v155, 0
	v_mov_b32_e32 v172, 0
	v_mov_b32_e32 v173, 0
	v_mov_b32_e32 v174, 0
	s_waitcnt vmcnt(12)
	v_permlane32_swap_b32_e32 v176, v180
	v_permlane32_swap_b32_e32 v177, v181
	v_permlane32_swap_b32_e32 v178, v182
	v_permlane32_swap_b32_e32 v179, v183
	v_permlane16_swap_b32_e32 v176, v180
	v_permlane16_swap_b32_e32 v177, v181
	v_permlane16_swap_b32_e32 v178, v182
	v_permlane16_swap_b32_e32 v179, v183
	v_permlane32_swap_b32_e32 v184, v188
	v_permlane32_swap_b32_e32 v185, v189
	v_permlane32_swap_b32_e32 v186, v190
	v_permlane32_swap_b32_e32 v187, v191
	v_permlane16_swap_b32_e32 v184, v188
	v_permlane16_swap_b32_e32 v185, v189
	v_permlane16_swap_b32_e32 v186, v190
	v_permlane16_swap_b32_e32 v187, v191
	v_pk_add_f32 v[124:125], v[124:125], v[176:177]
	s_nop 0
	v_cvt_pk_bf16_f32 v141, v124, v125
	v_mul_f32_e32 v125, v125, v125
	v_pk_add_f32 v[116:117], v[116:117], v[184:185]
	v_fmac_f32_e32 v125, v124, v124
	v_mul_f32_e32 v124, v117, v117
	v_pk_add_f32 v[126:127], v[126:127], v[178:179]
	v_pk_add_f32 v[156:157], v[118:119], v[186:187]
	v_fmac_f32_e32 v124, v116, v116
	v_fmac_f32_e32 v125, v126, v126
	v_fmac_f32_e32 v124, v156, v156
	v_pk_add_f32 v[120:121], v[120:121], v[180:181]
	v_pk_add_f32 v[112:113], v[112:113], v[188:189]
	v_fmac_f32_e32 v125, v127, v127
	v_fmac_f32_e32 v124, v157, v157
	v_fmac_f32_e32 v125, v120, v120
	v_fmac_f32_e32 v124, v112, v112
	v_pk_add_f32 v[122:123], v[122:123], v[182:183]
	v_pk_add_f32 v[158:159], v[114:115], v[190:191]
	v_fmac_f32_e32 v125, v121, v121
	v_fmac_f32_e32 v124, v113, v113
	v_fmac_f32_e32 v125, v122, v122
	v_fmac_f32_e32 v124, v158, v158
	v_fmac_f32_e32 v125, v123, v123
	v_fmac_f32_e32 v124, v159, v159
	v_cvt_pk_bf16_f32 v115, v112, v113
	v_add_f32_e32 v112, v125, v124
	ds_bpermute_b32 v113, v214, v112
	v_cvt_pk_bf16_f32 v162, v122, v123
	v_cvt_pk_bf16_f32 v114, v158, v159
	v_cvt_pk_bf16_f32 v118, v156, v157
	v_cvt_pk_bf16_f32 v117, v116, v117
	s_waitcnt lgkmcnt(0)
	v_add_f32_e32 v112, v112, v113
	ds_bpermute_b32 v113, v213, v112
	v_or_b32_e32 v122, s21, v145
	v_cvt_pk_bf16_f32 v160, v126, v127
	v_cvt_pk_bf16_f32 v161, v120, v121
	v_mov_b32_dpp v155, v117 row_ror:8 row_mask:0xf bank_mask:0xf
	v_mov_b32_dpp v172, v118 row_ror:8 row_mask:0xf bank_mask:0xf
	v_mov_b32_dpp v173, v115 row_ror:8 row_mask:0xf bank_mask:0xf
	v_mov_b32_dpp v174, v114 row_ror:8 row_mask:0xf bank_mask:0xf
	v_lshlrev_b32_e32 v122, 11, v122
	v_cndmask_b32_e64 v114, v141, v155, s[6:7]
	v_cndmask_b32_e64 v115, v160, v172, s[6:7]
	v_cndmask_b32_e64 v116, v161, v173, s[6:7]
	v_cndmask_b32_e64 v117, v162, v174, s[6:7]
	v_add_u32_e32 v123, v153, v122
	v_cndmask_b32_e64 v118, v155, v141, s[6:7]
	v_cndmask_b32_e64 v119, v172, v160, s[6:7]
	v_cndmask_b32_e64 v120, v173, v161, s[6:7]
	v_cndmask_b32_e64 v121, v174, v162, s[6:7]
	global_store_dwordx4 v123, v[114:117], s[24:25]
	s_nop 1
	v_add_u32_e32 v114, v152, v122
	global_store_dwordx4 v114, v[118:121], s[24:25]
	s_and_saveexec_b64 s[0:1], s[4:5]
	s_cbranch_execz .LBB0_556
	v_ashrrev_i32_e32 v141, 31, v140
	s_waitcnt lgkmcnt(0)
	v_add_f32_e32 v114, v112, v113
	v_lshl_add_u64 v[112:113], v[140:141], 2, s[78:79]
	global_atomic_add_f32 v[112:113], v114, off
; template <class T> DI T gld_nt(const void* base, unsigned off) { return __builtin_nontemporal_load((const T*)((const char*)base + off)); }
; DI u32x4 pk8(const f32x4& a, const f32x4& b) { u32x4 w; w.x = pk2(a[0], a[1]); w.y = pk2(a[2], a[3]); w.z = pk2(b[0], b[1]); w.w = pk2(b[2], b[3]); return w; }
; DI void unpk8(const u32x4& w, f32x4& a, f32x4& b) { a[0] = bf_lo(w.x); a[1] = bf_hi(w.x); a[2] = bf_lo(w.y); a[3] = bf_hi(w.y); b[0] = bf_lo(w.z); b[1] = bf_hi(w.z); b[2] = bf_lo(w.w); b[3] = bf_hi(w.w); }
;   DI void operator()(g8::Acc& acc, int pm, int pn, int wr, int wc, int fr, int fq) const {
;     ...
;         const int row = pm * BM + ai * HALF + wr * 64 + m * 16 + fr; float s = 0.f; u32x4 wv[2];
; #pragma unroll
;         for (int bj = 0; bj < 2; ++bj) {
;           const int col8 = pn * BM + wc * 64 + bj * 32 + fq * 8; const unsigned eo = (unsigned)row * DM + (unsigned)col8;
;           f32x4 r0, r1;
;           if (resf) { r0 = gld_nt<f32x4>(resf, eo * 4u); r1 = gld_nt<f32x4>(resf, eo * 4u + 16u); }
;           else unpk8(gld_nt<u32x4>(resb, eo * 2u), r0, r1);
;           const f32x4 o0 = r0 + acc[ai][bj][m][0], o1 = r1 + acc[ai][bj][m][1];
;           if (outf) { gst<f32x4>(outf, eo * 4u, o0); gst<f32x4>(outf, eo * 4u + 16u, o1); }
;           wv[bj] = pk8(o0, o1);
;           s += o0[0] * o0[0] + o0[1] * o0[1] + o0[2] * o0[2] + o0[3] * o0[3] + o1[0] * o1[0] + o1[1] * o1[1] + o1[2] * o1[2] + o1[3] * o1[3];
;         }
;         if (outb) st_rows16(outb, DM * 2u, (unsigned)(row - fr), (unsigned)(pn * BM + wc * 64), fr, fq, wv[0], wv[1]);
;         s += __shfl_xor(s, 16); s += __shfl_xor(s, 32);
;         if (fq == 0) atomicAdd(ssq + row, s);
.LBB0_556:
	s_or_b64 exec, exec, s[0:1]
	s_or_b32 s0, s21, 16
	v_or_b32_e32 v112, s0, v142
	s_waitcnt lgkmcnt(0)
	v_add_u32_e32 v249, 0x80000, v248
	global_load_dwordx4 v[176:179], v249, s[16:17] nt
	global_load_dwordx4 v[180:183], v249, s[16:17] offset:64 nt
	global_load_dwordx4 v[184:187], v249, s[16:17] offset:128 nt
	global_load_dwordx4 v[188:191], v249, s[16:17] offset:192 nt
	v_mov_b32_e32 v126, 0
	v_mov_b32_e32 v113, 0
	v_mov_b32_e32 v127, 0
	v_mov_b32_e32 v140, 0
	s_waitcnt vmcnt(14)
	v_permlane32_swap_b32_e32 v192, v196
	v_permlane32_swap_b32_e32 v193, v197
	v_permlane32_swap_b32_e32 v194, v198
	v_permlane32_swap_b32_e32 v195, v199
	v_permlane16_swap_b32_e32 v192, v196
	v_permlane16_swap_b32_e32 v193, v197
	v_permlane16_swap_b32_e32 v194, v198
	v_permlane16_swap_b32_e32 v195, v199
	v_permlane32_swap_b32_e32 v200, v204
	v_permlane32_swap_b32_e32 v201, v205
	v_permlane32_swap_b32_e32 v202, v206
	v_permlane32_swap_b32_e32 v203, v207
	v_permlane16_swap_b32_e32 v200, v204
	v_permlane16_swap_b32_e32 v201, v205
	v_permlane16_swap_b32_e32 v202, v206
	v_permlane16_swap_b32_e32 v203, v207
	v_pk_add_f32 v[108:109], v[108:109], v[192:193]
	v_pk_add_f32 v[104:105], v[104:105], v[196:197]
	v_cvt_pk_bf16_f32 v118, v108, v109
	v_mul_f32_e32 v109, v109, v109
	v_pk_add_f32 v[100:101], v[100:101], v[200:201]
	v_fmac_f32_e32 v109, v108, v108
	v_mul_f32_e32 v108, v101, v101
	v_pk_add_f32 v[110:111], v[110:111], v[194:195]
	v_pk_add_f32 v[114:115], v[102:103], v[202:203]
	v_fmac_f32_e32 v108, v100, v100
	v_fmac_f32_e32 v109, v110, v110
	v_fmac_f32_e32 v108, v114, v114
	v_pk_add_f32 v[96:97], v[96:97], v[204:205]
	v_fmac_f32_e32 v109, v111, v111
	v_fmac_f32_e32 v108, v115, v115
	v_fmac_f32_e32 v109, v104, v104
	v_fmac_f32_e32 v108, v96, v96
	v_pk_add_f32 v[106:107], v[106:107], v[198:199]
	v_pk_add_f32 v[116:117], v[98:99], v[206:207]
	v_fmac_f32_e32 v109, v105, v105
	v_fmac_f32_e32 v108, v97, v97
	v_fmac_f32_e32 v109, v106, v106
	v_fmac_f32_e32 v108, v116, v116
	v_fmac_f32_e32 v109, v107, v107
	v_fmac_f32_e32 v108, v117, v117
	v_cvt_pk_bf16_f32 v99, v96, v97
	v_add_f32_e32 v96, v109, v108
	ds_bpermute_b32 v97, v214, v96
	v_cvt_pk_bf16_f32 v121, v106, v107
	v_cvt_pk_bf16_f32 v98, v116, v117
	v_cvt_pk_bf16_f32 v102, v114, v115
	v_cvt_pk_bf16_f32 v101, v100, v101
	s_waitcnt lgkmcnt(0)
	v_add_f32_e32 v96, v96, v97
	ds_bpermute_b32 v97, v213, v96
	v_or_b32_e32 v106, s0, v145
	v_cvt_pk_bf16_f32 v119, v110, v111
	v_cvt_pk_bf16_f32 v120, v104, v105
	v_mov_b32_dpp v113, v101 row_ror:8 row_mask:0xf bank_mask:0xf
	v_mov_b32_dpp v126, v102 row_ror:8 row_mask:0xf bank_mask:0xf
	v_mov_b32_dpp v127, v99 row_ror:8 row_mask:0xf bank_mask:0xf
	v_mov_b32_dpp v140, v98 row_ror:8 row_mask:0xf bank_mask:0xf
	v_lshlrev_b32_e32 v106, 11, v106
	v_cndmask_b32_e64 v98, v118, v113, s[6:7]
	v_cndmask_b32_e64 v99, v119, v126, s[6:7]
	v_cndmask_b32_e64 v100, v120, v127, s[6:7]
	v_cndmask_b32_e64 v101, v121, v140, s[6:7]
	v_add_u32_e32 v107, v153, v106
	v_cndmask_b32_e64 v102, v113, v118, s[6:7]
	v_cndmask_b32_e64 v103, v126, v119, s[6:7]
	v_cndmask_b32_e64 v104, v127, v120, s[6:7]
	v_cndmask_b32_e64 v105, v140, v121, s[6:7]
	global_store_dwordx4 v107, v[98:101], s[24:25]
	s_nop 1
	v_add_u32_e32 v98, v152, v106
	global_store_dwordx4 v98, v[102:105], s[24:25]
	s_and_saveexec_b64 s[0:1], s[4:5]
	s_cbranch_execz .LBB0_558
	v_ashrrev_i32_e32 v113, 31, v112
	s_waitcnt lgkmcnt(0)
	v_add_f32_e32 v98, v96, v97
	v_lshl_add_u64 v[96:97], v[112:113], 2, s[78:79]
	global_atomic_add_f32 v[96:97], v98, off
.LBB0_558:
	s_or_b64 exec, exec, s[0:1]
	s_or_b32 s0, s21, 32
	v_or_b32_e32 v96, s0, v142
	s_waitcnt lgkmcnt(0)
	v_add_u32_e32 v249, 0x90000, v248
	global_load_dwordx4 v[192:195], v249, s[16:17] nt
	global_load_dwordx4 v[196:199], v249, s[16:17] offset:64 nt
	global_load_dwordx4 v[200:203], v249, s[16:17] offset:128 nt
	global_load_dwordx4 v[204:207], v249, s[16:17] offset:192 nt
	v_mov_b32_e32 v114, 0
	v_mov_b32_e32 v97, 0
	v_mov_b32_e32 v115, 0
	v_mov_b32_e32 v116, 0
	s_waitcnt vmcnt(16)
	v_permlane32_swap_b32_e32 v216, v220
	v_permlane32_swap_b32_e32 v217, v221
	v_permlane32_swap_b32_e32 v218, v222
	v_permlane32_swap_b32_e32 v219, v223
	v_permlane16_swap_b32_e32 v216, v220
	v_permlane16_swap_b32_e32 v217, v221
	v_permlane16_swap_b32_e32 v218, v222
	v_permlane16_swap_b32_e32 v219, v223
	v_permlane32_swap_b32_e32 v224, v228
	v_permlane32_swap_b32_e32 v225, v229
	v_permlane32_swap_b32_e32 v226, v230
	v_permlane32_swap_b32_e32 v227, v231
	v_permlane16_swap_b32_e32 v224, v228
	v_permlane16_swap_b32_e32 v225, v229
	v_permlane16_swap_b32_e32 v226, v230
	v_permlane16_swap_b32_e32 v227, v231
	v_pk_add_f32 v[92:93], v[92:93], v[216:217]
	v_pk_add_f32 v[88:89], v[88:89], v[220:221]
	v_cvt_pk_bf16_f32 v102, v92, v93
	v_mul_f32_e32 v93, v93, v93
	v_pk_add_f32 v[84:85], v[84:85], v[224:225]
	v_fmac_f32_e32 v93, v92, v92
	v_mul_f32_e32 v92, v85, v85
	v_pk_add_f32 v[94:95], v[94:95], v[218:219]
	v_pk_add_f32 v[98:99], v[86:87], v[226:227]
	v_fmac_f32_e32 v92, v84, v84
	v_fmac_f32_e32 v93, v94, v94
	v_fmac_f32_e32 v92, v98, v98
	v_pk_add_f32 v[80:81], v[80:81], v[228:229]
	v_fmac_f32_e32 v93, v95, v95
	v_fmac_f32_e32 v92, v99, v99
	v_fmac_f32_e32 v93, v88, v88
	v_fmac_f32_e32 v92, v80, v80
	v_pk_add_f32 v[90:91], v[90:91], v[222:223]
	v_pk_add_f32 v[100:101], v[82:83], v[230:231]
	v_fmac_f32_e32 v93, v89, v89
	v_fmac_f32_e32 v92, v81, v81
	v_fmac_f32_e32 v93, v90, v90
	v_fmac_f32_e32 v92, v100, v100
	v_fmac_f32_e32 v93, v91, v91
	v_fmac_f32_e32 v92, v101, v101
	v_cvt_pk_bf16_f32 v83, v80, v81
	v_add_f32_e32 v80, v93, v92
	ds_bpermute_b32 v81, v214, v80
	v_cvt_pk_bf16_f32 v105, v90, v91
	v_cvt_pk_bf16_f32 v82, v100, v101
	v_cvt_pk_bf16_f32 v86, v98, v99
	v_cvt_pk_bf16_f32 v85, v84, v85
	s_waitcnt lgkmcnt(0)
	v_add_f32_e32 v80, v80, v81
	ds_bpermute_b32 v81, v213, v80
	v_or_b32_e32 v90, s0, v145
	v_cvt_pk_bf16_f32 v103, v94, v95
	v_cvt_pk_bf16_f32 v104, v88, v89
	v_mov_b32_dpp v97, v85 row_ror:8 row_mask:0xf bank_mask:0xf
	v_mov_b32_dpp v114, v86 row_ror:8 row_mask:0xf bank_mask:0xf
	v_mov_b32_dpp v115, v83 row_ror:8 row_mask:0xf bank_mask:0xf
	v_mov_b32_dpp v116, v82 row_ror:8 row_mask:0xf bank_mask:0xf
	v_lshlrev_b32_e32 v90, 11, v90
	v_cndmask_b32_e64 v82, v102, v97, s[6:7]
	v_cndmask_b32_e64 v83, v103, v114, s[6:7]
	v_cndmask_b32_e64 v84, v104, v115, s[6:7]
	v_cndmask_b32_e64 v85, v105, v116, s[6:7]
	v_add_u32_e32 v91, v153, v90
	v_cndmask_b32_e64 v86, v97, v102, s[6:7]
	v_cndmask_b32_e64 v87, v114, v103, s[6:7]
	v_cndmask_b32_e64 v88, v115, v104, s[6:7]
	v_cndmask_b32_e64 v89, v116, v105, s[6:7]
	global_store_dwordx4 v91, v[82:85], s[24:25]
	s_nop 1
	v_add_u32_e32 v82, v152, v90
	global_store_dwordx4 v82, v[86:89], s[24:25]
	s_and_saveexec_b64 s[0:1], s[4:5]
	s_cbranch_execz .LBB0_560
	v_ashrrev_i32_e32 v97, 31, v96
	s_waitcnt lgkmcnt(0)
	v_add_f32_e32 v82, v80, v81
	v_lshl_add_u64 v[80:81], v[96:97], 2, s[78:79]
	global_atomic_add_f32 v[80:81], v82, off
; template <class T> DI T gld_nt(const void* base, unsigned off) { return __builtin_nontemporal_load((const T*)((const char*)base + off)); }
; DI u32x4 pk8(const f32x4& a, const f32x4& b) { u32x4 w; w.x = pk2(a[0], a[1]); w.y = pk2(a[2], a[3]); w.z = pk2(b[0], b[1]); w.w = pk2(b[2], b[3]); return w; }
; DI void unpk8(const u32x4& w, f32x4& a, f32x4& b) { a[0] = bf_lo(w.x); a[1] = bf_hi(w.x); a[2] = bf_lo(w.y); a[3] = bf_hi(w.y); b[0] = bf_lo(w.z); b[1] = bf_hi(w.z); b[2] = bf_lo(w.w); b[3] = bf_hi(w.w); }
;   DI void operator()(g8::Acc& acc, int pm, int pn, int wr, int wc, int fr, int fq) const {
;     ...
;         const int row = pm * BM + ai * HALF + wr * 64 + m * 16 + fr; float s = 0.f; u32x4 wv[2];
; #pragma unroll
;         for (int bj = 0; bj < 2; ++bj) {
;           const int col8 = pn * BM + wc * 64 + bj * 32 + fq * 8; const unsigned eo = (unsigned)row * DM + (unsigned)col8;
;           f32x4 r0, r1;
;           if (resf) { r0 = gld_nt<f32x4>(resf, eo * 4u); r1 = gld_nt<f32x4>(resf, eo * 4u + 16u); }
;           else unpk8(gld_nt<u32x4>(resb, eo * 2u), r0, r1);
;           const f32x4 o0 = r0 + acc[ai][bj][m][0], o1 = r1 + acc[ai][bj][m][1];
;           if (outf) { gst<f32x4>(outf, eo * 4u, o0); gst<f32x4>(outf, eo * 4u + 16u, o1); }
;           wv[bj] = pk8(o0, o1);
;           s += o0[0] * o0[0] + o0[1] * o0[1] + o0[2] * o0[2] + o0[3] * o0[3] + o1[0] * o1[0] + o1[1] * o1[1] + o1[2] * o1[2] + o1[3] * o1[3];
;         }
;         if (outb) st_rows16(outb, DM * 2u, (unsigned)(row - fr), (unsigned)(pn * BM + wc * 64), fr, fq, wv[0], wv[1]);
;         s += __shfl_xor(s, 16); s += __shfl_xor(s, 32);
;         if (fq == 0) atomicAdd(ssq + row, s);
.LBB0_560:
	s_or_b64 exec, exec, s[0:1]
	s_or_b32 s0, s21, 48
	v_or_b32_e32 v80, s0, v142
	s_waitcnt lgkmcnt(0)
	v_add_u32_e32 v249, 0xa0000, v248
	global_load_dwordx4 v[216:219], v249, s[16:17] nt
	global_load_dwordx4 v[220:223], v249, s[16:17] offset:64 nt
	global_load_dwordx4 v[224:227], v249, s[16:17] offset:128 nt
	global_load_dwordx4 v[228:231], v249, s[16:17] offset:192 nt
	v_mov_b32_e32 v98, 0
	v_mov_b32_e32 v81, 0
	v_mov_b32_e32 v99, 0
	v_mov_b32_e32 v100, 0
	s_waitcnt vmcnt(18)
	v_permlane32_swap_b32_e32 v232, v236
	v_permlane32_swap_b32_e32 v233, v237
	v_permlane32_swap_b32_e32 v234, v238
	v_permlane32_swap_b32_e32 v235, v239
	v_permlane16_swap_b32_e32 v232, v236
	v_permlane16_swap_b32_e32 v233, v237
	v_permlane16_swap_b32_e32 v234, v238
	v_permlane16_swap_b32_e32 v235, v239
	v_permlane32_swap_b32_e32 v240, v244
	v_permlane32_swap_b32_e32 v241, v245
	v_permlane32_swap_b32_e32 v242, v246
	v_permlane32_swap_b32_e32 v243, v247
	v_permlane16_swap_b32_e32 v240, v244
	v_permlane16_swap_b32_e32 v241, v245
	v_permlane16_swap_b32_e32 v242, v246
	v_permlane16_swap_b32_e32 v243, v247
	v_pk_add_f32 v[76:77], v[76:77], v[232:233]
	v_pk_add_f32 v[72:73], v[72:73], v[236:237]
	v_cvt_pk_bf16_f32 v86, v76, v77
	v_mul_f32_e32 v77, v77, v77
	v_pk_add_f32 v[68:69], v[68:69], v[240:241]
	v_fmac_f32_e32 v77, v76, v76
	v_mul_f32_e32 v76, v69, v69
	v_pk_add_f32 v[78:79], v[78:79], v[234:235]
	v_pk_add_f32 v[82:83], v[70:71], v[242:243]
	v_fmac_f32_e32 v76, v68, v68
	v_fmac_f32_e32 v77, v78, v78
	v_fmac_f32_e32 v76, v82, v82
	v_pk_add_f32 v[64:65], v[64:65], v[244:245]
	v_fmac_f32_e32 v77, v79, v79
	v_fmac_f32_e32 v76, v83, v83
	v_fmac_f32_e32 v77, v72, v72
	v_fmac_f32_e32 v76, v64, v64
	v_pk_add_f32 v[74:75], v[74:75], v[238:239]
	v_pk_add_f32 v[84:85], v[66:67], v[246:247]
	v_fmac_f32_e32 v77, v73, v73
	v_fmac_f32_e32 v76, v65, v65
	v_fmac_f32_e32 v77, v74, v74
	v_fmac_f32_e32 v76, v84, v84
	v_fmac_f32_e32 v77, v75, v75
	v_fmac_f32_e32 v76, v85, v85
	v_cvt_pk_bf16_f32 v67, v64, v65
	v_add_f32_e32 v64, v77, v76
	ds_bpermute_b32 v65, v214, v64
	v_cvt_pk_bf16_f32 v89, v74, v75
	v_cvt_pk_bf16_f32 v66, v84, v85
	v_cvt_pk_bf16_f32 v70, v82, v83
	v_cvt_pk_bf16_f32 v69, v68, v69
	s_waitcnt lgkmcnt(0)
	v_add_f32_e32 v64, v64, v65
	ds_bpermute_b32 v65, v213, v64
	v_or_b32_e32 v74, s0, v145
	v_cvt_pk_bf16_f32 v87, v78, v79
	v_cvt_pk_bf16_f32 v88, v72, v73
	v_mov_b32_dpp v81, v69 row_ror:8 row_mask:0xf bank_mask:0xf
	v_mov_b32_dpp v98, v70 row_ror:8 row_mask:0xf bank_mask:0xf
	v_mov_b32_dpp v99, v67 row_ror:8 row_mask:0xf bank_mask:0xf
	v_mov_b32_dpp v100, v66 row_ror:8 row_mask:0xf bank_mask:0xf
	v_lshlrev_b32_e32 v74, 11, v74
	v_cndmask_b32_e64 v66, v86, v81, s[6:7]
	v_cndmask_b32_e64 v67, v87, v98, s[6:7]
	v_cndmask_b32_e64 v68, v88, v99, s[6:7]
	v_cndmask_b32_e64 v69, v89, v100, s[6:7]
	v_add_u32_e32 v75, v153, v74
	v_cndmask_b32_e64 v70, v81, v86, s[6:7]
	v_cndmask_b32_e64 v71, v98, v87, s[6:7]
	v_cndmask_b32_e64 v72, v99, v88, s[6:7]
	v_cndmask_b32_e64 v73, v100, v89, s[6:7]
	global_store_dwordx4 v75, v[66:69], s[24:25]
	s_nop 1
	v_add_u32_e32 v66, v152, v74
	global_store_dwordx4 v66, v[70:73], s[24:25]
	s_and_saveexec_b64 s[0:1], s[4:5]
	s_cbranch_execz .LBB0_562
	v_ashrrev_i32_e32 v81, 31, v80
	s_waitcnt lgkmcnt(0)
	v_add_f32_e32 v66, v64, v65
	v_lshl_add_u64 v[64:65], v[80:81], 2, s[78:79]
	global_atomic_add_f32 v[64:65], v66, off
.LBB0_562:
	s_or_b64 exec, exec, s[0:1]
	s_add_i32 s0, s21, 0x80
	v_or_b32_e32 v64, s0, v142
	s_waitcnt lgkmcnt(0)
	v_add_u32_e32 v249, 0xb0000, v248
	global_load_dwordx4 v[232:235], v249, s[16:17] nt
	global_load_dwordx4 v[236:239], v249, s[16:17] offset:64 nt
	global_load_dwordx4 v[240:243], v249, s[16:17] offset:128 nt
	global_load_dwordx4 v[244:247], v249, s[16:17] offset:192 nt
	v_mov_b32_e32 v82, 0
	v_mov_b32_e32 v65, 0
	v_mov_b32_e32 v83, 0
	v_mov_b32_e32 v84, 0
	s_waitcnt vmcnt(18)
	v_permlane32_swap_b32_e32 v176, v180
	v_permlane32_swap_b32_e32 v177, v181
	v_permlane32_swap_b32_e32 v178, v182
	v_permlane32_swap_b32_e32 v179, v183
	v_permlane16_swap_b32_e32 v176, v180
	v_permlane16_swap_b32_e32 v177, v181
	v_permlane16_swap_b32_e32 v178, v182
	v_permlane16_swap_b32_e32 v179, v183
	v_permlane32_swap_b32_e32 v184, v188
	v_permlane32_swap_b32_e32 v185, v189
	v_permlane32_swap_b32_e32 v186, v190
	v_permlane32_swap_b32_e32 v187, v191
	v_permlane16_swap_b32_e32 v184, v188
	v_permlane16_swap_b32_e32 v185, v189
	v_permlane16_swap_b32_e32 v186, v190
	v_permlane16_swap_b32_e32 v187, v191
	v_pk_add_f32 v[60:61], v[60:61], v[176:177]
	v_pk_add_f32 v[56:57], v[56:57], v[180:181]
	v_cvt_pk_bf16_f32 v70, v60, v61
	v_mul_f32_e32 v61, v61, v61
	v_pk_add_f32 v[52:53], v[52:53], v[184:185]
	v_fmac_f32_e32 v61, v60, v60
	v_mul_f32_e32 v60, v53, v53
	v_pk_add_f32 v[62:63], v[62:63], v[178:179]
	v_pk_add_f32 v[66:67], v[54:55], v[186:187]
	v_fmac_f32_e32 v60, v52, v52
	v_fmac_f32_e32 v61, v62, v62
	v_fmac_f32_e32 v60, v66, v66
	v_pk_add_f32 v[48:49], v[48:49], v[188:189]
	v_fmac_f32_e32 v61, v63, v63
	v_fmac_f32_e32 v60, v67, v67
	v_fmac_f32_e32 v61, v56, v56
	v_fmac_f32_e32 v60, v48, v48
	v_pk_add_f32 v[58:59], v[58:59], v[182:183]
	v_pk_add_f32 v[68:69], v[50:51], v[190:191]
	v_fmac_f32_e32 v61, v57, v57
	v_fmac_f32_e32 v60, v49, v49
	v_fmac_f32_e32 v61, v58, v58
	v_fmac_f32_e32 v60, v68, v68
	v_fmac_f32_e32 v61, v59, v59
	v_fmac_f32_e32 v60, v69, v69
	v_cvt_pk_bf16_f32 v51, v48, v49
	v_add_f32_e32 v48, v61, v60
	ds_bpermute_b32 v49, v214, v48
	v_cvt_pk_bf16_f32 v73, v58, v59
	v_cvt_pk_bf16_f32 v50, v68, v69
	v_cvt_pk_bf16_f32 v54, v66, v67
	v_cvt_pk_bf16_f32 v53, v52, v53
	s_waitcnt lgkmcnt(0)
	v_add_f32_e32 v48, v48, v49
	ds_bpermute_b32 v49, v213, v48
	v_or_b32_e32 v58, s0, v145
	v_cvt_pk_bf16_f32 v71, v62, v63
	v_cvt_pk_bf16_f32 v72, v56, v57
	v_mov_b32_dpp v65, v53 row_ror:8 row_mask:0xf bank_mask:0xf
	v_mov_b32_dpp v82, v54 row_ror:8 row_mask:0xf bank_mask:0xf
	v_mov_b32_dpp v83, v51 row_ror:8 row_mask:0xf bank_mask:0xf
	v_mov_b32_dpp v84, v50 row_ror:8 row_mask:0xf bank_mask:0xf
	v_lshlrev_b32_e32 v58, 11, v58
	v_cndmask_b32_e64 v50, v70, v65, s[6:7]
	v_cndmask_b32_e64 v51, v71, v82, s[6:7]
	v_cndmask_b32_e64 v52, v72, v83, s[6:7]
	v_cndmask_b32_e64 v53, v73, v84, s[6:7]
	v_add_u32_e32 v59, v153, v58
	v_cndmask_b32_e64 v54, v65, v70, s[6:7]
	v_cndmask_b32_e64 v55, v82, v71, s[6:7]
	v_cndmask_b32_e64 v56, v83, v72, s[6:7]
	v_cndmask_b32_e64 v57, v84, v73, s[6:7]
	global_store_dwordx4 v59, v[50:53], s[24:25]
	s_nop 1
	v_add_u32_e32 v50, v152, v58
	global_store_dwordx4 v50, v[54:57], s[24:25]
	s_and_saveexec_b64 s[0:1], s[4:5]
	s_cbranch_execz .LBB0_564
	v_ashrrev_i32_e32 v65, 31, v64
	s_waitcnt lgkmcnt(0)
	v_add_f32_e32 v50, v48, v49
	v_lshl_add_u64 v[48:49], v[64:65], 2, s[78:79]
	global_atomic_add_f32 v[48:49], v50, off
; template <class T> DI T gld_nt(const void* base, unsigned off) { return __builtin_nontemporal_load((const T*)((const char*)base + off)); }
; DI u32x4 pk8(const f32x4& a, const f32x4& b) { u32x4 w; w.x = pk2(a[0], a[1]); w.y = pk2(a[2], a[3]); w.z = pk2(b[0], b[1]); w.w = pk2(b[2], b[3]); return w; }
; DI void unpk8(const u32x4& w, f32x4& a, f32x4& b) { a[0] = bf_lo(w.x); a[1] = bf_hi(w.x); a[2] = bf_lo(w.y); a[3] = bf_hi(w.y); b[0] = bf_lo(w.z); b[1] = bf_hi(w.z); b[2] = bf_lo(w.w); b[3] = bf_hi(w.w); }
;   DI void operator()(g8::Acc& acc, int pm, int pn, int wr, int wc, int fr, int fq) const {
;     ...
;         const int row = pm * BM + ai * HALF + wr * 64 + m * 16 + fr; float s = 0.f; u32x4 wv[2];
; #pragma unroll
;         for (int bj = 0; bj < 2; ++bj) {
;           const int col8 = pn * BM + wc * 64 + bj * 32 + fq * 8; const unsigned eo = (unsigned)row * DM + (unsigned)col8;
;           f32x4 r0, r1;
;           if (resf) { r0 = gld_nt<f32x4>(resf, eo * 4u); r1 = gld_nt<f32x4>(resf, eo * 4u + 16u); }
;           else unpk8(gld_nt<u32x4>(resb, eo * 2u), r0, r1);
;           const f32x4 o0 = r0 + acc[ai][bj][m][0], o1 = r1 + acc[ai][bj][m][1];
;           if (outf) { gst<f32x4>(outf, eo * 4u, o0); gst<f32x4>(outf, eo * 4u + 16u, o1); }
;           wv[bj] = pk8(o0, o1);
;           s += o0[0] * o0[0] + o0[1] * o0[1] + o0[2] * o0[2] + o0[3] * o0[3] + o1[0] * o1[0] + o1[1] * o1[1] + o1[2] * o1[2] + o1[3] * o1[3];
;         }
;         if (outb) st_rows16(outb, DM * 2u, (unsigned)(row - fr), (unsigned)(pn * BM + wc * 64), fr, fq, wv[0], wv[1]);
;         s += __shfl_xor(s, 16); s += __shfl_xor(s, 32);
;         if (fq == 0) atomicAdd(ssq + row, s);
.LBB0_564:
	s_or_b64 exec, exec, s[0:1]
	s_add_i32 s0, s21, 0x90
	v_or_b32_e32 v48, s0, v142
	s_waitcnt lgkmcnt(0)
	v_mov_b32_e32 v66, 0
	v_mov_b32_e32 v49, 0
	v_mov_b32_e32 v67, 0
	v_mov_b32_e32 v68, 0
	s_waitcnt vmcnt(14)
	v_permlane32_swap_b32_e32 v192, v196
	v_permlane32_swap_b32_e32 v193, v197
	v_permlane32_swap_b32_e32 v194, v198
	v_permlane32_swap_b32_e32 v195, v199
	v_permlane16_swap_b32_e32 v192, v196
	v_permlane16_swap_b32_e32 v193, v197
	v_permlane16_swap_b32_e32 v194, v198
	v_permlane16_swap_b32_e32 v195, v199
	v_permlane32_swap_b32_e32 v200, v204
	v_permlane32_swap_b32_e32 v201, v205
	v_permlane32_swap_b32_e32 v202, v206
	v_permlane32_swap_b32_e32 v203, v207
	v_permlane16_swap_b32_e32 v200, v204
	v_permlane16_swap_b32_e32 v201, v205
	v_permlane16_swap_b32_e32 v202, v206
	v_permlane16_swap_b32_e32 v203, v207
	v_pk_add_f32 v[44:45], v[44:45], v[192:193]
	v_pk_add_f32 v[40:41], v[40:41], v[196:197]
	v_cvt_pk_bf16_f32 v54, v44, v45
	v_mul_f32_e32 v45, v45, v45
	v_pk_add_f32 v[36:37], v[36:37], v[200:201]
	v_fmac_f32_e32 v45, v44, v44
	v_mul_f32_e32 v44, v37, v37
	v_pk_add_f32 v[46:47], v[46:47], v[194:195]
	v_pk_add_f32 v[50:51], v[38:39], v[202:203]
	v_fmac_f32_e32 v44, v36, v36
	v_fmac_f32_e32 v45, v46, v46
	v_fmac_f32_e32 v44, v50, v50
	v_pk_add_f32 v[32:33], v[32:33], v[204:205]
	v_fmac_f32_e32 v45, v47, v47
	v_fmac_f32_e32 v44, v51, v51
	v_fmac_f32_e32 v45, v40, v40
	v_fmac_f32_e32 v44, v32, v32
	v_pk_add_f32 v[42:43], v[42:43], v[198:199]
	v_pk_add_f32 v[52:53], v[34:35], v[206:207]
	v_fmac_f32_e32 v45, v41, v41
	v_fmac_f32_e32 v44, v33, v33
	v_fmac_f32_e32 v45, v42, v42
	v_fmac_f32_e32 v44, v52, v52
	v_fmac_f32_e32 v45, v43, v43
	v_fmac_f32_e32 v44, v53, v53
	v_cvt_pk_bf16_f32 v35, v32, v33
	v_add_f32_e32 v32, v45, v44
	ds_bpermute_b32 v33, v214, v32
	v_cvt_pk_bf16_f32 v57, v42, v43
	v_cvt_pk_bf16_f32 v34, v52, v53
	v_cvt_pk_bf16_f32 v38, v50, v51
	v_cvt_pk_bf16_f32 v37, v36, v37
	s_waitcnt lgkmcnt(0)
	v_add_f32_e32 v32, v32, v33
	ds_bpermute_b32 v33, v213, v32
	v_or_b32_e32 v42, s0, v145
	v_cvt_pk_bf16_f32 v55, v46, v47
	v_cvt_pk_bf16_f32 v56, v40, v41
	v_mov_b32_dpp v49, v37 row_ror:8 row_mask:0xf bank_mask:0xf
	v_mov_b32_dpp v66, v38 row_ror:8 row_mask:0xf bank_mask:0xf
	v_mov_b32_dpp v67, v35 row_ror:8 row_mask:0xf bank_mask:0xf
	v_mov_b32_dpp v68, v34 row_ror:8 row_mask:0xf bank_mask:0xf
	v_lshlrev_b32_e32 v42, 11, v42
	v_cndmask_b32_e64 v34, v54, v49, s[6:7]
	v_cndmask_b32_e64 v35, v55, v66, s[6:7]
	v_cndmask_b32_e64 v36, v56, v67, s[6:7]
	v_cndmask_b32_e64 v37, v57, v68, s[6:7]
	v_add_u32_e32 v43, v153, v42
	v_cndmask_b32_e64 v38, v49, v54, s[6:7]
	v_cndmask_b32_e64 v39, v66, v55, s[6:7]
	v_cndmask_b32_e64 v40, v67, v56, s[6:7]
	v_cndmask_b32_e64 v41, v68, v57, s[6:7]
	global_store_dwordx4 v43, v[34:37], s[24:25]
	s_nop 1
	v_add_u32_e32 v34, v152, v42
	global_store_dwordx4 v34, v[38:41], s[24:25]
	s_and_saveexec_b64 s[0:1], s[4:5]
	s_cbranch_execz .LBB0_566
	v_ashrrev_i32_e32 v49, 31, v48
	s_waitcnt lgkmcnt(0)
	v_add_f32_e32 v34, v32, v33
	v_lshl_add_u64 v[32:33], v[48:49], 2, s[78:79]
	global_atomic_add_f32 v[32:33], v34, off
; template <class T> DI T gld_nt(const void* base, unsigned off) { return __builtin_nontemporal_load((const T*)((const char*)base + off)); }
; DI u32x4 pk8(const f32x4& a, const f32x4& b) { u32x4 w; w.x = pk2(a[0], a[1]); w.y = pk2(a[2], a[3]); w.z = pk2(b[0], b[1]); w.w = pk2(b[2], b[3]); return w; }
; DI void unpk8(const u32x4& w, f32x4& a, f32x4& b) { a[0] = bf_lo(w.x); a[1] = bf_hi(w.x); a[2] = bf_lo(w.y); a[3] = bf_hi(w.y); b[0] = bf_lo(w.z); b[1] = bf_hi(w.z); b[2] = bf_lo(w.w); b[3] = bf_hi(w.w); }
;   DI void operator()(g8::Acc& acc, int pm, int pn, int wr, int wc, int fr, int fq) const {
;     ...
;         const int row = pm * BM + ai * HALF + wr * 64 + m * 16 + fr; float s = 0.f; u32x4 wv[2];
; #pragma unroll
;         for (int bj = 0; bj < 2; ++bj) {
;           const int col8 = pn * BM + wc * 64 + bj * 32 + fq * 8; const unsigned eo = (unsigned)row * DM + (unsigned)col8;
;           f32x4 r0, r1;
;           if (resf) { r0 = gld_nt<f32x4>(resf, eo * 4u); r1 = gld_nt<f32x4>(resf, eo * 4u + 16u); }
;           else unpk8(gld_nt<u32x4>(resb, eo * 2u), r0, r1);
;           const f32x4 o0 = r0 + acc[ai][bj][m][0], o1 = r1 + acc[ai][bj][m][1];
;           if (outf) { gst<f32x4>(outf, eo * 4u, o0); gst<f32x4>(outf, eo * 4u + 16u, o1); }
;           wv[bj] = pk8(o0, o1);
;           s += o0[0] * o0[0] + o0[1] * o0[1] + o0[2] * o0[2] + o0[3] * o0[3] + o1[0] * o1[0] + o1[1] * o1[1] + o1[2] * o1[2] + o1[3] * o1[3];
;         }
;         if (outb) st_rows16(outb, DM * 2u, (unsigned)(row - fr), (unsigned)(pn * BM + wc * 64), fr, fq, wv[0], wv[1]);
;         s += __shfl_xor(s, 16); s += __shfl_xor(s, 32);
;         if (fq == 0) atomicAdd(ssq + row, s);
.LBB0_566:
	s_or_b64 exec, exec, s[0:1]
	s_add_i32 s0, s21, 0xa0
	v_or_b32_e32 v32, s0, v142
	s_waitcnt lgkmcnt(0)
	v_mov_b32_e32 v50, 0
	v_mov_b32_e32 v33, 0
	v_mov_b32_e32 v51, 0
	v_mov_b32_e32 v52, 0
	s_waitcnt vmcnt(10)
	v_permlane32_swap_b32_e32 v216, v220
	v_permlane32_swap_b32_e32 v217, v221
	v_permlane32_swap_b32_e32 v218, v222
	v_permlane32_swap_b32_e32 v219, v223
	v_permlane16_swap_b32_e32 v216, v220
	v_permlane16_swap_b32_e32 v217, v221
	v_permlane16_swap_b32_e32 v218, v222
	v_permlane16_swap_b32_e32 v219, v223
	v_permlane32_swap_b32_e32 v224, v228
	v_permlane32_swap_b32_e32 v225, v229
	v_permlane32_swap_b32_e32 v226, v230
	v_permlane32_swap_b32_e32 v227, v231
	v_permlane16_swap_b32_e32 v224, v228
	v_permlane16_swap_b32_e32 v225, v229
	v_permlane16_swap_b32_e32 v226, v230
	v_permlane16_swap_b32_e32 v227, v231
	v_pk_add_f32 v[28:29], v[28:29], v[216:217]
	v_pk_add_f32 v[24:25], v[24:25], v[220:221]
	v_cvt_pk_bf16_f32 v38, v28, v29
	v_mul_f32_e32 v29, v29, v29
	v_pk_add_f32 v[20:21], v[20:21], v[224:225]
	v_fmac_f32_e32 v29, v28, v28
	v_mul_f32_e32 v28, v21, v21
	v_pk_add_f32 v[30:31], v[30:31], v[218:219]
	v_pk_add_f32 v[34:35], v[22:23], v[226:227]
	v_fmac_f32_e32 v28, v20, v20
	v_fmac_f32_e32 v29, v30, v30
	v_fmac_f32_e32 v28, v34, v34
	v_pk_add_f32 v[16:17], v[16:17], v[228:229]
	v_fmac_f32_e32 v29, v31, v31
	v_fmac_f32_e32 v28, v35, v35
	v_fmac_f32_e32 v29, v24, v24
	v_fmac_f32_e32 v28, v16, v16
	v_pk_add_f32 v[26:27], v[26:27], v[222:223]
	v_pk_add_f32 v[36:37], v[18:19], v[230:231]
	v_fmac_f32_e32 v29, v25, v25
	v_fmac_f32_e32 v28, v17, v17
	v_fmac_f32_e32 v29, v26, v26
	v_fmac_f32_e32 v28, v36, v36
	v_fmac_f32_e32 v29, v27, v27
	v_fmac_f32_e32 v28, v37, v37
	v_cvt_pk_bf16_f32 v19, v16, v17
	v_add_f32_e32 v16, v29, v28
	ds_bpermute_b32 v17, v214, v16
	v_cvt_pk_bf16_f32 v41, v26, v27
	v_cvt_pk_bf16_f32 v18, v36, v37
	v_cvt_pk_bf16_f32 v22, v34, v35
	v_cvt_pk_bf16_f32 v21, v20, v21
	s_waitcnt lgkmcnt(0)
	v_add_f32_e32 v16, v16, v17
	ds_bpermute_b32 v17, v213, v16
	v_or_b32_e32 v26, s0, v145
	v_cvt_pk_bf16_f32 v39, v30, v31
	v_cvt_pk_bf16_f32 v40, v24, v25
	v_mov_b32_dpp v33, v21 row_ror:8 row_mask:0xf bank_mask:0xf
	v_mov_b32_dpp v50, v22 row_ror:8 row_mask:0xf bank_mask:0xf
	v_mov_b32_dpp v51, v19 row_ror:8 row_mask:0xf bank_mask:0xf
	v_mov_b32_dpp v52, v18 row_ror:8 row_mask:0xf bank_mask:0xf
	v_lshlrev_b32_e32 v26, 11, v26
	v_cndmask_b32_e64 v18, v38, v33, s[6:7]
	v_cndmask_b32_e64 v19, v39, v50, s[6:7]
	v_cndmask_b32_e64 v20, v40, v51, s[6:7]
	v_cndmask_b32_e64 v21, v41, v52, s[6:7]
	v_add_u32_e32 v27, v153, v26
	v_cndmask_b32_e64 v22, v33, v38, s[6:7]
	v_cndmask_b32_e64 v23, v50, v39, s[6:7]
	v_cndmask_b32_e64 v24, v51, v40, s[6:7]
	v_cndmask_b32_e64 v25, v52, v41, s[6:7]
	global_store_dwordx4 v27, v[18:21], s[24:25]
	s_nop 1
	v_add_u32_e32 v18, v152, v26
	global_store_dwordx4 v18, v[22:25], s[24:25]
	s_and_saveexec_b64 s[0:1], s[4:5]
	s_cbranch_execz .LBB0_568
	v_ashrrev_i32_e32 v33, 31, v32
	s_waitcnt lgkmcnt(0)
	v_add_f32_e32 v18, v16, v17
	v_lshl_add_u64 v[16:17], v[32:33], 2, s[78:79]
	global_atomic_add_f32 v[16:17], v18, off
.LBB0_568:
	s_or_b64 exec, exec, s[0:1]
	s_addk_i32 s21, 0xb0
	v_or_b32_e32 v16, s21, v142
	s_waitcnt lgkmcnt(0)
	v_mov_b32_e32 v34, 0
	v_mov_b32_e32 v17, 0
	v_mov_b32_e32 v35, 0
	v_mov_b32_e32 v36, 0
	s_waitcnt vmcnt(6)
	v_permlane32_swap_b32_e32 v232, v236
	v_permlane32_swap_b32_e32 v233, v237
	v_permlane32_swap_b32_e32 v234, v238
	v_permlane32_swap_b32_e32 v235, v239
	v_permlane16_swap_b32_e32 v232, v236
	v_permlane16_swap_b32_e32 v233, v237
	v_permlane16_swap_b32_e32 v234, v238
	v_permlane16_swap_b32_e32 v235, v239
	v_permlane32_swap_b32_e32 v240, v244
	v_permlane32_swap_b32_e32 v241, v245
	v_permlane32_swap_b32_e32 v242, v246
	v_permlane32_swap_b32_e32 v243, v247
	v_permlane16_swap_b32_e32 v240, v244
	v_permlane16_swap_b32_e32 v241, v245
	v_permlane16_swap_b32_e32 v242, v246
	v_permlane16_swap_b32_e32 v243, v247
	v_pk_add_f32 v[12:13], v[12:13], v[232:233]
	v_pk_add_f32 v[8:9], v[8:9], v[236:237]
	v_cvt_pk_bf16_f32 v22, v12, v13
	v_mul_f32_e32 v13, v13, v13
	v_pk_add_f32 v[4:5], v[4:5], v[240:241]
	v_fmac_f32_e32 v13, v12, v12
	v_mul_f32_e32 v12, v5, v5
	v_pk_add_f32 v[14:15], v[14:15], v[234:235]
	v_pk_add_f32 v[18:19], v[6:7], v[242:243]
	v_fmac_f32_e32 v12, v4, v4
	v_fmac_f32_e32 v13, v14, v14
	v_fmac_f32_e32 v12, v18, v18
	v_pk_add_f32 v[0:1], v[0:1], v[244:245]
	v_fmac_f32_e32 v13, v15, v15
	v_fmac_f32_e32 v12, v19, v19
	v_fmac_f32_e32 v13, v8, v8
	v_fmac_f32_e32 v12, v0, v0
	v_pk_add_f32 v[10:11], v[10:11], v[238:239]
	v_pk_add_f32 v[20:21], v[2:3], v[246:247]
	v_fmac_f32_e32 v13, v9, v9
	v_fmac_f32_e32 v12, v1, v1
	v_fmac_f32_e32 v13, v10, v10
	v_fmac_f32_e32 v12, v20, v20
	v_fmac_f32_e32 v13, v11, v11
	v_fmac_f32_e32 v12, v21, v21
	v_cvt_pk_bf16_f32 v3, v0, v1
	v_add_f32_e32 v0, v13, v12
	ds_bpermute_b32 v1, v214, v0
	v_cvt_pk_bf16_f32 v25, v10, v11
	v_cvt_pk_bf16_f32 v2, v20, v21
	v_cvt_pk_bf16_f32 v6, v18, v19
	v_cvt_pk_bf16_f32 v5, v4, v5
	s_waitcnt lgkmcnt(0)
	v_add_f32_e32 v0, v0, v1
	ds_bpermute_b32 v1, v213, v0
	v_or_b32_e32 v10, s21, v145
	v_cvt_pk_bf16_f32 v23, v14, v15
	v_cvt_pk_bf16_f32 v24, v8, v9
	v_mov_b32_dpp v17, v5 row_ror:8 row_mask:0xf bank_mask:0xf
	v_mov_b32_dpp v34, v6 row_ror:8 row_mask:0xf bank_mask:0xf
	v_mov_b32_dpp v35, v3 row_ror:8 row_mask:0xf bank_mask:0xf
	v_mov_b32_dpp v36, v2 row_ror:8 row_mask:0xf bank_mask:0xf
	v_lshlrev_b32_e32 v10, 11, v10
	v_cndmask_b32_e64 v2, v22, v17, s[6:7]
	v_cndmask_b32_e64 v3, v23, v34, s[6:7]
	v_cndmask_b32_e64 v4, v24, v35, s[6:7]
	v_cndmask_b32_e64 v5, v25, v36, s[6:7]
	v_add_u32_e32 v11, v153, v10
	v_cndmask_b32_e64 v6, v17, v22, s[6:7]
	v_cndmask_b32_e64 v7, v34, v23, s[6:7]
	v_cndmask_b32_e64 v8, v35, v24, s[6:7]
	v_cndmask_b32_e64 v9, v36, v25, s[6:7]
	global_store_dwordx4 v11, v[2:5], s[24:25]
	s_nop 1
	v_add_u32_e32 v2, v152, v10
	global_store_dwordx4 v2, v[6:9], s[24:25]
	s_and_saveexec_b64 s[0:1], s[4:5]
	s_cbranch_execz .LBB0_570
	v_ashrrev_i32_e32 v17, 31, v16
	s_waitcnt lgkmcnt(0)
	v_add_f32_e32 v2, v0, v1
	v_lshl_add_u64 v[0:1], v[16:17], 2, s[78:79]
	global_atomic_add_f32 v[0:1], v2, off
